# stack + GLA decay stage: raw q/k via 8 transposing LDS reads, scaled q/k stored transposed with b64 writes (48 fewer LDS instructions per step)
# baseline (speedup 1.0000x reference)
; #define LAS __attribute__((address_space(3)))
; __device__ __forceinline__ unsigned cvtpk(float lo, float hi) { f32x2 v = {lo, hi}; bf16x2_t b = __builtin_convertvector(v, bf16x2_t); return __builtin_bit_cast(unsigned, b); }
; __device__ __forceinline__ void gla_unit(LAS char* lds0, int b, int h, int dvh, bf16_t* Z, bf16_t* OT, const float* afw, const float* afb, const float* abw, const float* abb, bool dry) {
;     int tid = threadIdx.x; asm volatile("" : "+v"(tid)); const int lane = tid & 63, r32 = lane & 31, hi = lane >> 5; const int wid = __builtin_amdgcn_readfirstlane(tid >> 6);
;     const int dir = wid >> 2, wg = wid & 3, tg = tid & 255;
;     LAS char* lds = lds0 + dir * G_GROUP;
;     const int g16 = (lane >> 4) & 1, q4 = (lane & 15) >> 2, p4 = lane & 3;
;     const int I = wg >> 1, J = wg & 1;
;     const float* w2 = dir ? abw : afw; const float* bb = dir ? abb : afb;
;     bf16x8 w2b;
;     { u32x4 t; t.x = cvtpk(w2[(8 * hi + 0) * 256 + h * 64 + 32 * J + r32], w2[(8 * hi + 1) * 256 + h * 64 + 32 * J + r32]);
;       t.y = cvtpk(w2[(8 * hi + 2) * 256 + h * 64 + 32 * J + r32], w2[(8 * hi + 3) * 256 + h * 64 + 32 * J + r32]);
;       t.z = cvtpk(w2[(8 * hi + 4) * 256 + h * 64 + 32 * J + r32], w2[(8 * hi + 5) * 256 + h * 64 + 32 * J + r32]);
;       t.w = cvtpk(w2[(8 * hi + 6) * 256 + h * 64 + 32 * J + r32], w2[(8 * hi + 7) * 256 + h * 64 + 32 * J + r32]);
;       w2b = __builtin_bit_cast(bf16x8, t); }
;     const float bias = bb[h * 64 + 32 * J + r32];
;     const int zcol_a = dir ? ZAB : ZAF;
;     f32x16 S = {};
;     for (int i = tg; i < GARR / 4; i += 256) ((LAS unsigned*)(lds + G_SB))[i] = 0u;
;     u32x4 pq0, pq1, pk0, pk1, pv0, pv1; u32x2 pa;
;     const int lr = tg >> 3, lc = tg & 7, ar = tg >> 2, ac = tg & 3;
;     ...
;     GLA_PREFETCH(0);
.LBB0_401:
	v_mov_b32_e32 v6, v182
	s_bfe_u32 s8, s97, 0x20001
	v_readfirstlane_b32 s28, v6
	s_lshr_b32 s0, s28, 8
	s_mul_i32 s0, s0, 0x10a00
	s_add_i32 s76, s0, 0
	s_bfe_u32 s42, s28, 0x10006
	s_cmpk_lt_u32 s28, 0x100
	s_cselect_b64 s[0:1], -1, 0
	s_cmpk_gt_u32 s28, 0xff
	v_readlane_b32 s52, v254, 59
	s_cselect_b64 s[16:17], -1, 0
	s_and_b64 s[2:3], s[0:1], exec
	v_readlane_b32 s54, v254, 61
	v_readlane_b32 s58, v255, 1
	v_readlane_b32 s55, v254, 62
	v_readlane_b32 s59, v255, 2
	s_cselect_b32 s2, s54, s58
	s_cselect_b32 s3, s55, s59
	s_add_u32 s2, s2, s94
	s_addc_u32 s3, s3, s95
	v_readlane_b32 s56, v254, 63
	s_and_b64 s[14:15], s[0:1], exec
	v_readlane_b32 s44, v254, 55
	v_readlane_b32 s57, v255, 0
	v_readlane_b32 s45, v254, 56
	s_cselect_b32 s15, s56, s44
	v_readlane_b32 s24, v255, 36
	v_bfe_u32 v16, v6, 3, 5
	s_cselect_b32 s14, s57, s45
	v_readlane_b32 s25, v255, 37
	s_add_u32 s24, s15, s24
	v_and_b32_e32 v14, 31, v6
	v_bfe_u32 v15, v6, 5, 1
	v_xor_b32_e32 v0, 63, v16
	s_addc_u32 s25, s14, s25
	s_lshl_b32 s43, s42, 5
	v_cndmask_b32_e64 v114, v0, v16, s[0:1]
	v_lshlrev_b32_e32 v0, 11, v15
	s_lshl_b32 s77, s8, 6
	v_or_b32_e32 v18, s43, v14
	v_or3_b32 v0, v0, s77, v18
	v_lshlrev_b32_e32 v0, 2, v0
	v_lshl_add_u64 v[2:3], s[2:3], 0, v[0:1]
	global_load_dword v17, v0, s[2:3]
	global_load_dword v19, v0, s[2:3] offset:1024
	global_load_dword v21, v0, s[2:3] offset:2048
	s_nop 0
	global_load_dword v0, v0, s[2:3] offset:3072
	s_movk_i32 s2, 0x1000
	v_add_co_u32_e32 v2, vcc, s2, v2
	s_ashr_i32 s2, s97, 3
	s_nop 0
	v_addc_co_u32_e32 v3, vcc, 0, v3, vcc
	s_lshr_b32 s40, s28, 7
	s_bfe_u32 s84, s28, 0x10007
	global_load_dword v22, v[2:3], off
	global_load_dword v23, v[2:3], off offset:1024
	global_load_dword v24, v[2:3], off offset:2048
	s_nop 0
	global_load_dword v3, v[2:3], off offset:3072
	v_and_b32_e32 v2, 0xff, v6
	s_and_b64 s[14:15], s[0:1], exec
	v_lshrrev_b32_e32 v25, 5, v6
	v_bfe_u32 v26, v6, 2, 2
	v_and_b32_e32 v27, 16, v6
	v_and_b32_e32 v28, 3, v6
	v_and_b32_e32 v7, 7, v6
	v_bfe_u32 v29, v6, 2, 6
	v_xor_b32_e32 v6, 31, v16
	v_or_b32_e32 v8, 32, v16
	v_lshl_add_u32 v2, v2, 2, s76
	s_mul_hi_i32 s14, s2, 0x900
	s_mul_i32 s15, s2, 0x900
	s_movk_i32 s2, 0x380
	s_cselect_b32 s34, 0, 0xc0
	ds_write2st64_b32 v2, v1, v1 offset0:180 offset1:184
	ds_write2st64_b32 v2, v1, v1 offset0:188 offset1:192
	ds_write2st64_b32 v2, v1, v1 offset0:196 offset1:200
	ds_write2st64_b32 v2, v1, v1 offset0:204 offset1:208
	ds_write_b32 v2, v1 offset:54272
	v_cndmask_b32_e64 v118, v6, v8, s[0:1]
	v_or_b32_e32 v2, s77, v18
	s_cselect_b32 s28, s2, 0x3a0
	s_or_b32 s34, s34, s15
	v_mov_b64_e32 v[4:5], s[88:89]
	v_lshlrev_b32_e32 v2, 2, v2
	v_or_b32_e32 v6, s34, v114
	v_or_b32_e32 v8, s34, v118
	v_lshlrev_b32_e32 v20, 3, v7
	v_lshlrev_b32_e32 v116, 4, v7
	global_load_dword v2, v2, s[24:25]
	v_mad_u64_u32 v[6:7], s[24:25], v6, s13, v[4:5]
	v_mad_u64_u32 v[8:9], s[24:25], v8, s13, v[4:5]
	s_mov_b32 s3, s9
	s_lshl_b32 s2, s8, 7
	v_mad_i32_i24 v7, s14, v204, v7
	v_mad_i32_i24 v9, s14, v204, v9
	v_lshl_add_u64 v[10:11], v[6:7], 0, s[2:3]
	v_lshl_add_u64 v[12:13], v[8:9], 0, s[2:3]
	s_lshl_b32 s3, s97, 6
	s_lshl_b32 s8, s8, 8
	s_and_b32 s3, s3, 64
	s_mov_b32 s29, 0
	v_lshl_add_u64 v[6:7], v[6:7], 0, s[8:9]
	s_lshl_b32 s24, s3, 1
	s_mov_b32 s25, s9
	v_mov_b32_e32 v117, v1
	v_lshl_add_u64 v[6:7], v[6:7], 0, s[24:25]
	v_lshl_add_u64 v[8:9], v[8:9], 0, s[8:9]
	v_lshl_add_u64 v[10:11], v[10:11], 0, v[116:117]
	v_lshl_add_u64 v[12:13], v[12:13], 0, v[116:117]
	v_lshl_add_u64 v[6:7], v[6:7], 0, v[116:117]
	v_lshl_add_u64 v[8:9], v[8:9], 0, s[24:25]
	global_load_dwordx4 v[70:73], v[10:11], off offset:2048
	global_load_dwordx4 v[74:77], v[10:11], off offset:2560
	global_load_dwordx4 v[78:81], v[12:13], off offset:2048
	global_load_dwordx4 v[82:85], v[12:13], off offset:2560
	v_lshl_add_u64 v[8:9], v[8:9], 0, v[116:117]
	global_load_dwordx4 v[86:89], v[6:7], off offset:3072
	global_load_dwordx4 v[90:93], v[8:9], off offset:3072
	v_and_b32_e32 v6, 64, v203
	v_add_u32_e32 v6, 64, v6
	v_lshlrev_b32_e32 v30, 3, v15
	v_mov_b32_e32 v31, s76
	s_movk_i32 s44, 0x90
	v_mad_u32_u24 v136, v18, s44, v31
	v_or_b32_e32 v44, v30, v26
	v_readlane_b32 s46, v254, 57
	v_readlane_b32 s47, v254, 58
	v_mul_u32_u24_e32 v154, 0x90, v44
	v_or_b32_e32 v44, 16, v30
	v_or_b32_e32 v46, 32, v30
	v_or_b32_e32 v30, 48, v30
	v_readlane_b32 s53, v254, 60
	v_mad_u32_u24 v115, v16, s44, v31
	s_or_b32 s18, s84, s42
	v_and_b32_e32 v244, 0xff, v182
	v_lshl_add_u32 v241, v244, 4, v31
	v_mov_b32_e32 v198, 0x200
	v_mov_b32_e32 v199, 0
	v_mov_b32_e32 v247, v244
	v_mul_u32_u24_e32 v245, 0x1c72, v247
	v_lshrrev_b32_e32 v245, 16, v245
	v_mul_u32_u24_e32 v246, 9, v245
	v_sub_u32_e32 v246, v247, v246
	v_cmp_eq_u32_e32 vcc, 8, v246
	v_cndmask_b32_e64 v246, v246, 0, vcc
	v_lshlrev_b32_e32 v246, 4, v246
	v_add_u32_e32 v200, 0x800, v246
	v_mov_b32_e32 v201, 0
	v_add_u32_e32 v192, 0xc00, v246
	v_mov_b32_e32 v193, 0
	v_xor_b32_e32 v246, 63, v245
	v_cndmask_b32_e64 v184, v246, v245, s[0:1]
	v_add_u32_e32 v247, 0x100, v244
	v_mul_u32_u24_e32 v245, 0x1c72, v247
	v_lshrrev_b32_e32 v245, 16, v245
	v_mul_u32_u24_e32 v246, 9, v245
	v_sub_u32_e32 v246, v247, v246
	v_cmp_eq_u32_e32 vcc, 8, v246
	v_cndmask_b32_e64 v246, v246, 0, vcc
	v_lshlrev_b32_e32 v246, 4, v246
	v_add_u32_e32 v248, 0x800, v246
	v_mov_b32_e32 v249, 0
	v_add_u32_e32 v194, 0xc00, v246
	v_mov_b32_e32 v195, 0
	v_xor_b32_e32 v246, 63, v245
	v_cndmask_b32_e64 v185, v246, v245, s[0:1]
	v_add_u32_e32 v247, 0x200, v244
	v_mul_u32_u24_e32 v245, 0x1c72, v247
	v_lshrrev_b32_e32 v245, 16, v245
	v_mul_u32_u24_e32 v246, 9, v245
	v_sub_u32_e32 v246, v247, v246
	v_cmp_eq_u32_e32 vcc, 8, v246
	v_cndmask_b32_e64 v246, v246, 0, vcc
	v_lshlrev_b32_e32 v246, 4, v246
	v_add_u32_e32 v250, 0x800, v246
	v_mov_b32_e32 v251, 0
	v_add_u32_e32 v196, 0xc00, v246
	v_mov_b32_e32 v197, 0
	v_xor_b32_e32 v246, 63, v245
	v_cndmask_b32_e64 v205, v246, v245, s[0:1]
	s_waitcnt vmcnt(0)
; #define LAS __attribute__((address_space(3)))
; __device__ __forceinline__ unsigned cvtpk(float lo, float hi) { f32x2 v = {lo, hi}; bf16x2_t b = __builtin_convertvector(v, bf16x2_t); return __builtin_bit_cast(unsigned, b); }
; __device__ __forceinline__ void gla_unit(LAS char* lds0, int b, int h, int dvh, bf16_t* Z, bf16_t* OT, const float* afw, const float* afb, const float* abw, const float* abb, bool dry) {
;     int tid = threadIdx.x; asm volatile("" : "+v"(tid)); const int lane = tid & 63, r32 = lane & 31, hi = lane >> 5; const int wid = __builtin_amdgcn_readfirstlane(tid >> 6);
;     const int dir = wid >> 2, wg = wid & 3, tg = tid & 255;
;     LAS char* lds = lds0 + dir * G_GROUP;
;     const int g16 = (lane >> 4) & 1, q4 = (lane & 15) >> 2, p4 = lane & 3;
;     const int I = wg >> 1, J = wg & 1;
;     const float* w2 = dir ? abw : afw; const float* bb = dir ? abb : afb;
;     bf16x8 w2b;
;     { u32x4 t; t.x = cvtpk(w2[(8 * hi + 0) * 256 + h * 64 + 32 * J + r32], w2[(8 * hi + 1) * 256 + h * 64 + 32 * J + r32]);
;       t.y = cvtpk(w2[(8 * hi + 2) * 256 + h * 64 + 32 * J + r32], w2[(8 * hi + 3) * 256 + h * 64 + 32 * J + r32]);
;       t.z = cvtpk(w2[(8 * hi + 4) * 256 + h * 64 + 32 * J + r32], w2[(8 * hi + 5) * 256 + h * 64 + 32 * J + r32]);
;       t.w = cvtpk(w2[(8 * hi + 6) * 256 + h * 64 + 32 * J + r32], w2[(8 * hi + 7) * 256 + h * 64 + 32 * J + r32]);
;       w2b = __builtin_bit_cast(bf16x8, t); }
;     const float bias = bb[h * 64 + 32 * J + r32];
;     const int zcol_a = dir ? ZAB : ZAF;
;     f32x16 S = {};
;     for (int i = tg; i < GARR / 4; i += 256) ((LAS unsigned*)(lds + G_SB))[i] = 0u;
;     u32x4 pq0, pq1, pk0, pk1, pv0, pv1; u32x2 pa;
;     const int lr = tg >> 3, lc = tg & 7, ar = tg >> 2, ac = tg & 3;
;     ...
;     GLA_PREFETCH(0);
	v_cvt_pk_bf16_f32 v67, v21, v0
	v_xor_b32_e32 v0, 63, v29
	v_cndmask_b32_e64 v120, v0, v29, s[0:1]
	v_or_b32_e32 v0, s34, v120
	v_mad_u64_u32 v[4:5], s[34:35], v0, s13, v[4:5]
	v_mad_i32_i24 v5, s14, v204, v5
	v_lshl_add_u64 v[4:5], v[4:5], 0, s[28:29]
	v_lshlrev_b32_e32 v0, 3, v28
	v_lshl_add_u64 v[4:5], v[4:5], 0, v[0:1]
	global_load_dwordx2 v[126:127], v[4:5], off
	s_add_u32 s34, s88, s28
	s_addc_u32 s35, s89, 0
	v_lshl_add_u64 v[122:123], s[34:35], 0, v[0:1]
	v_readlane_b32 s34, v252, 21
	v_readlane_b32 s35, v252, 22
	s_add_u32 s8, s34, s8
	s_addc_u32 s25, s35, 0
	s_add_u32 s24, s8, s24
	s_addc_u32 s25, s25, 0
	v_lshl_add_u64 v[124:125], s[24:25], 0, v[116:117]
	s_add_i32 s24, s76, 0x10500
	s_lshl_b32 s28, s42, 7
	v_xor_b32_e32 v5, 32, v203
	s_lshl_b32 s25, s84, 8
	s_add_i32 s28, s24, s28
	s_lshl_b32 s8, s84, 5
	v_cmp_lt_i32_e32 vcc, v5, v6
	s_add_i32 s25, s28, s25
	v_cvt_pk_bf16_f32 v68, v22, v23
	v_cndmask_b32_e32 v5, v203, v5, vcc
	v_lshlrev_b32_e32 v6, 2, v18
	s_cmp_eq_u32 s84, 0
	v_lshl_or_b32 v23, v15, 2, s8
	v_lshl_add_u32 v21, v29, 5, s76
	v_lshlrev_b32_e32 v119, 2, v5
	v_lshlrev_b32_e32 v5, 2, v14
	v_add_u32_e32 v132, s24, v6
	s_cselect_b64 s[34:35], -1, 0
	s_add_i32 s24, s76, 0x10400
	v_mul_u32_u24_e32 v29, 0x48, v23
	v_cvt_pk_bf16_f32 v69, v24, v3
	v_lshlrev_b32_e32 v3, 2, v28
	v_or_b32_e32 v4, s8, v14
	v_add_u32_e32 v121, s25, v5
	v_lshlrev_b32_e32 v24, 1, v18
	s_cmp_le_u32 s42, s84
	s_movk_i32 s25, 0xff72
	v_lshlrev_b32_e32 v29, 1, v29
	v_lshl_add_u32 v22, v4, 5, s76
	v_lshlrev_b32_e32 v117, 4, v15
	v_add_u32_e32 v133, s28, v5
	v_bitop3_b32 v5, s40, 1, v25 bitop3:0xc8
	s_cselect_b64 s[78:79], -1, 0
	v_mad_u32_u24 v135, v4, s44, v31
	v_or3_b32 v4, v3, v27, s43
	v_mad_i32_i24 v25, v18, s25, v136
	v_lshl_add_u32 v238, v23, 1, v136
	v_add_u32_e32 v239, v136, v117
	s_lshl_b32 s25, s42, 6
	v_or3_b32 v3, v27, s8, v3
	v_add3_u32 v138, s76, v24, v29
	v_or_b32_e32 v29, 2, v23
	s_add_i32 s8, s76, 0x10420
	v_lshl_add_u32 v137, v4, 1, s76
	v_add_u32_e32 v222, v23, v26
	v_mul_u32_u24_e32 v222, 0x90, v222
	v_add_u32_e32 v222, v137, v222
	s_add_i32 s25, s76, s25
	v_lshl_add_u32 v27, v3, 1, s76
	v_or_b32_e32 v24, 1, v23
	v_or_b32_e32 v31, 3, v23
	v_or_b32_e32 v32, 8, v23
	v_or_b32_e32 v33, 9, v23
	v_or_b32_e32 v34, 10, v23
	v_or_b32_e32 v35, 11, v23
	v_or_b32_e32 v36, 16, v23
	v_or_b32_e32 v37, 17, v23
	v_or_b32_e32 v38, 18, v23
	v_or_b32_e32 v39, 19, v23
	v_or_b32_e32 v40, 24, v23
	v_or_b32_e32 v41, 25, v23
	v_or_b32_e32 v42, 26, v23
	v_or_b32_e32 v43, 27, v23
	v_lshlrev_b32_e32 v45, 1, v44
	v_or_b32_e32 v44, v44, v26
	v_lshlrev_b32_e32 v47, 1, v46
	v_or_b32_e32 v46, v46, v26
	v_or_b32_e32 v26, v30, v26
	v_cmp_lt_u32_e64 s[46:47], v29, v18
	v_add_u32_e32 v29, s8, v117
	s_add_i32 s8, s76, 0x10440
	s_add_i32 s76, s76, 0x10460
	v_cvt_pk_bf16_f32 v66, v17, v19
	v_add_u32_e32 v19, 0x1200, v115
	v_lshl_add_u32 v28, v14, 1, s25
	v_mul_u32_u24_e32 v44, 0x90, v44
	v_mul_u32_u24_e32 v46, 0x90, v46
	v_lshlrev_b32_e32 v48, 1, v30
	v_mul_u32_u24_e32 v26, 0x90, v26
	v_cmp_lt_u32_e64 s[42:43], v23, v18
	v_mul_u32_u24_e32 v23, 0x90, v23
	v_cmp_lt_u32_e64 s[44:45], v24, v18
	v_cmp_lt_u32_e64 s[50:51], v31, v18
	v_cmp_lt_u32_e64 s[52:53], v32, v18
	v_cmp_lt_u32_e64 s[54:55], v33, v18
	v_cmp_lt_u32_e64 s[56:57], v34, v18
	v_cmp_lt_u32_e64 s[58:59], v35, v18
	v_cmp_lt_u32_e64 s[60:61], v36, v18
	v_cmp_lt_u32_e64 s[62:63], v37, v18
	v_cmp_lt_u32_e64 s[64:65], v38, v18
	v_cmp_lt_u32_e64 s[66:67], v39, v18
	v_cmp_lt_u32_e64 s[68:69], v40, v18
	v_cmp_lt_u32_e64 s[70:71], v41, v18
	v_cmp_lt_u32_e64 s[72:73], v42, v18
	v_cmp_lt_u32_e64 s[74:75], v43, v18
	s_lshl_b32 s25, s84, 7
	v_add_u32_e32 v24, s24, v117
	v_add_u32_e32 v30, s8, v117
	v_add_u32_e32 v31, s76, v117
	v_mov_b32_e32 v18, 0
	v_cmp_eq_u32_e64 s[38:39], 0, v15
	v_cmp_eq_u32_e64 s[40:41], 0, v5
	v_add_u32_e32 v134, s24, v6
	v_mov_b32_e32 v3, v2
	v_mov_b32_e32 v4, v2
	v_mov_b32_e32 v5, v2
	v_mov_b32_e32 v6, v2
	v_mov_b32_e32 v7, v2
	v_mov_b32_e32 v8, v2
	v_mov_b32_e32 v9, v2
	v_mov_b32_e32 v10, v2
	v_mov_b32_e32 v11, v2
	v_mov_b32_e32 v12, v2
	v_mov_b32_e32 v13, v2
	v_mov_b32_e32 v14, v2
	v_mov_b32_e32 v15, v2
	v_mov_b32_e32 v16, v2
	v_mov_b32_e32 v17, v2
	v_add_u32_e32 v139, 0x90, v138
	s_waitcnt lgkmcnt(5)
	v_add_u32_e32 v140, 0x120, v138
	v_add_u32_e32 v141, 0x1b0, v138
	v_add_u32_e32 v142, 0x480, v138
	v_add_u32_e32 v143, 0x510, v138
	v_add_u32_e32 v144, 0x5a0, v138
	v_add_u32_e32 v145, 0x630, v138
	v_add_u32_e32 v146, 0x900, v138
	v_add_u32_e32 v147, 0x990, v138
	v_add_u32_e32 v148, 0xa20, v138
	v_add_u32_e32 v149, 0xab0, v138
	v_add_u32_e32 v150, 0xd80, v138
	v_add_u32_e32 v151, 0xe10, v138
	v_add_u32_e32 v152, 0xea0, v138
	v_add_u32_e32 v153, 0xf30, v138
	v_add_u32_e32 v155, v21, v0
	s_lshl_b32 s8, s77, 1
	v_lshlrev_b32_e32 v0, 1, v20
	s_lshl_b32 s24, s2, 1
	s_lshl_b32 s84, s3, 1
	v_add_u32_e32 v156, v22, v117
	v_add_u32_e32 v157, v137, v44
	v_add_u32_e32 v158, v137, v46
	v_add_u32_e32 v159, v137, v26
	v_add_u32_e32 v160, v25, v23
	v_add_u32_e32 v161, v28, v23
	v_add_u32_e32 v162, s25, v24
	v_add_u32_e32 v163, s25, v29
	v_add_u32_e32 v164, s25, v30
	v_add_u32_e32 v165, s25, v31
	v_add_u32_e32 v166, v27, v154
	v_add_u32_e32 v167, v19, v116
	v_add_u32_e32 v168, v135, v45
	v_add_u32_e32 v169, v135, v47
	v_add_u32_e32 v170, v135, v48
	s_mov_b32 s76, s29
	v_mov_b32_e32 v19, v18
	v_mov_b32_e32 v20, v18
	v_mov_b32_e32 v21, v18
	v_mov_b32_e32 v22, v18
	v_mov_b32_e32 v23, v18
	v_mov_b32_e32 v24, v18
	v_mov_b32_e32 v25, v18
	v_mov_b32_e32 v26, v18
	v_mov_b32_e32 v27, v18
	v_mov_b32_e32 v28, v18
	v_mov_b32_e32 v29, v18
	v_mov_b32_e32 v30, v18
	v_mov_b32_e32 v31, v18
	v_mov_b32_e32 v32, v18
	v_mov_b32_e32 v33, v18
	s_branch .LBB0_403

; #define LAS __attribute__((address_space(3)))
; __device__ __forceinline__ bf16_t f2bf(float f) { return (bf16_t)(cvtpk(f, 0.f) & 0xffffu); }
; __device__ __forceinline__ int crow(int r, int hi) { return (r & 3) + 8 * (r >> 2) + 4 * hi; }
; __device__ __forceinline__ void gla_unit(LAS char* lds0, int b, int h, int dvh, bf16_t* Z, bf16_t* OT, const float* afw, const float* afb, const float* abw, const float* abb, bool dry) {
;     ...
;             for (int r = 0; r < 16; ++r) { const int i_ = 32 * I + crow(r, hi), j_ = 32 * J + r32;
;                 ((LAS bf16_t*)(lds + G_AM))[i_ * (GP / 2) + j_] = f2bf((i_ >= j_) ? Ac[r] : 0.f); }
;         }
;         asm volatile("s_waitcnt lgkmcnt(0)\n\ts_barrier" ::: "memory");
.LBB0_420:
	s_nop 9
	ds_read_b128 v[54:57], v239 offset:46080
	ds_read_b128 v[174:177], v239 offset:46112
	ds_read_b128 v[178:181], v239 offset:46144
	ds_read_b128 v[188:191], v239 offset:46176
	v_cndmask_b32_e64 v34, v34, 0, s[42:43]
	v_cndmask_b32_e64 v35, v35, 0, s[44:45]
	v_cndmask_b32_e64 v36, v36, 0, s[46:47]
	v_cndmask_b32_e64 v37, v37, 0, s[50:51]
	v_cvt_pk_bf16_f32 v242, v34, v35
	v_cvt_pk_bf16_f32 v243, v36, v37
	ds_write_b64 v238, v[242:243] offset:36864
	s_waitcnt lgkmcnt(4)
	v_mfma_f32_32x32x16_bf16 v[50:65], v[50:53], v[54:57], 0
	v_cndmask_b32_e64 v38, v38, 0, s[52:53]
	v_cndmask_b32_e64 v39, v39, 0, s[54:55]
	v_cndmask_b32_e64 v40, v40, 0, s[56:57]
	v_cndmask_b32_e64 v41, v41, 0, s[58:59]
	v_cvt_pk_bf16_f32 v242, v38, v39
	v_cvt_pk_bf16_f32 v243, v40, v41
	ds_write_b64 v238, v[242:243] offset:36880
	s_waitcnt lgkmcnt(4)
	v_mfma_f32_32x32x16_bf16 v[50:65], v[106:109], v[174:177], v[50:65]
	v_cndmask_b32_e64 v42, v42, 0, s[60:61]
	v_cndmask_b32_e64 v43, v43, 0, s[62:63]
	v_cndmask_b32_e64 v44, v44, 0, s[64:65]
	v_cndmask_b32_e64 v45, v45, 0, s[66:67]
	v_cvt_pk_bf16_f32 v242, v42, v43
	v_cvt_pk_bf16_f32 v243, v44, v45
	ds_write_b64 v238, v[242:243] offset:36896
	s_waitcnt lgkmcnt(4)
	v_mfma_f32_32x32x16_bf16 v[50:65], v[102:105], v[178:181], v[50:65]
	v_cndmask_b32_e64 v46, v46, 0, s[68:69]
	v_cndmask_b32_e64 v47, v47, 0, s[70:71]
	v_cndmask_b32_e64 v48, v48, 0, s[72:73]
	v_cndmask_b32_e64 v49, v49, 0, s[74:75]
	v_cvt_pk_bf16_f32 v242, v46, v47
	v_cvt_pk_bf16_f32 v243, v48, v49
	ds_write_b64 v238, v[242:243] offset:36912
	s_waitcnt lgkmcnt(4)
	v_mfma_f32_32x32x16_bf16 v[50:65], v[110:113], v[188:191], v[50:65]
	s_waitcnt lgkmcnt(0)
	s_barrier
	s_cmpk_eq_i32 s29, 0xffdd
	s_cbranch_scc1 .Lg7_nqk
	v_readfirstlane_b32 s96, v241
	s_mov_b32 m0, s96
	s_nop 0
	global_load_lds_dwordx4 v[70:71], off
	s_add_i32 s98, s96, 0x1000
	s_mov_b32 m0, s98
	s_nop 0
	global_load_lds_dwordx4 v[72:73], off
	v_lshl_add_u64 v[82:83], v[70:71], 0, v[198:199]
	v_lshl_add_u64 v[84:85], v[72:73], 0, v[198:199]
	s_add_i32 s98, s96, 0x2400
	s_mov_b32 m0, s98
	s_nop 0
	global_load_lds_dwordx4 v[82:83], off
	s_add_i32 s98, s96, 0x3400
	s_mov_b32 m0, s98
	s_nop 0
	global_load_lds_dwordx4 v[84:85], off
	s_cmp_lg_u32 s18, 0
	s_cbranch_scc1 .Lg7_nqk
	s_add_i32 s98, s96, 0x2000
	s_mov_b32 m0, s98
	s_nop 0
	global_load_lds_dwordx4 v[74:75], off
	v_lshl_add_u64 v[82:83], v[74:75], 0, v[198:199]
	s_add_i32 s98, s96, 0x4400
	s_mov_b32 m0, s98
	s_nop 0
	global_load_lds_dwordx4 v[82:83], off
